# LRU gates: bias add+scale folded into one fma (32 sites); LRU y_b epilogue packing via v_cvt_pk_bf16_f32
# speedup vs baseline: 1.0027x; 1.0027x over previous
; __device__ __forceinline__ void mix_phase(LAS unsigned char* lds, const Params& p, const int layer) {
;     ...
;             int xb = 0, ab = 0;
;             for (int u = u0; u < NUB; u += G) {
;                 const int s_ = u >> 4, r0 = mix_tile_row0(s_);
;                 const bool prt = s_ < 128;
;                 LAS float* XC = XC3 + xb * (33792 / 4); LAS bf16* At = At2 + ab * (17408 / 2);
;                 const int xbn = (xb == 2) ? 0 : xb + 1, abn = ab ^ 1;
;                 const v4u sgc0 = *(const v4u*)(PROJ + (size_t)(r0 + yrow) * NC + C_GB + c0 + yc16), sgc1 = *(const v4u*)(PROJ + (size_t)(r0 + yrow) * NC + C_GB + c0 + yc16 + 8);
;             f32x4 accr[4], acci[4];
; #pragma unroll
;             for (int m = 0; m < 4; ++m) { accr[m] = (f32x4){0.f, 0.f, 0.f, 0.f}; acci[m] = (f32x4){0.f, 0.f, 0.f, 0.f}; }
; #pragma unroll
;             for (int ks = 0; ks < 4; ++ks)
; #pragma unroll
;                 for (int m = 0; m < 4; ++m) { const bf16x8 a = *(const LAS bf16x8*)(At + (m * 16 + fr) * 136 + ks * 32 + fq * 8);
;                     accr[m] = __builtin_amdgcn_mfma_f32_16x16x32_bf16(a, ba[ks], accr[m], 0, 0, 0);
;                     acci[m] = __builtin_amdgcn_mfma_f32_16x16x32_bf16(a, bx[ks], acci[m], 0, 0, 0); }
;             float hl[4][4], pl[4][4];
;             float Hc = 0.f, Pc = 1.f;
;             const int gq = prt ? fq : (fq & 1);
;             float h0s[4] = {0.f, 0.f, 0.f, 0.f};
;             if (!prt) {
; #pragma unroll
;                 for (int m = 0; m < 4; ++m) h0s[m] = p.in[4][(size_t)(layer * 128 + ((r0 - NP) >> 3) + 2 * m + (fq >> 1)) * LW + ch];
;             }
; #pragma unroll
;             for (int m = 0; m < 4; ++m) {
;                 float h_[4], P_[4];
; #pragma unroll
;                 for (int j = 0; j < 4; ++j) { const float xa = XC[(m * 16 + fq * 4 + j) * 132 + cw + fr];
;                     const float rg = mix_sigmoid(accr[m][j] + bav), ig = mix_sigmoid(acci[m][j] + bxv), la = -rg * c8v, x2 = 2.0f * la;
;                     const float Pj = __expf(la);
;                     const float q_ = 1.f + x2 * (0.5f + x2 * (1.f / 6 + x2 * (1.f / 24 + x2 * (1.f / 120 + x2 * (1.f / 720 + x2 * (1.f / 5040))))));
;                     const float om = (x2 > -0.3f) ? -x2 * q_ : 1.0f - Pj * Pj;
;                     P_[j] = Pj; h_[j] = __builtin_amdgcn_sqrtf(om) * (ig * xa); }
; #pragma unroll
.LBB0_406:
	v_lshlrev_b32_e32 v0, 3, v137
	v_lshlrev_b32_e32 v66, 4, v130
	v_lshlrev_b32_e32 v70, 1, v0
	v_lshrrev_b32_e32 v0, 1, v137
	v_readlane_b32 s3, v248, 33
	v_and_b32_e32 v140, 0x70, v66
	v_and_b32_e32 v66, 64, v223
	v_or_b32_e32 v228, s3, v0
	v_add_u32_e32 v0, -16, v223
	v_cmp_lt_i32_e32 vcc, v0, v66
	v_ashrrev_i32_e32 v133, 31, v132
	s_mov_b64 s[6:7], 0x26308000
	v_cndmask_b32_e32 v0, v0, v223, vcc
	v_lshlrev_b32_e32 v229, 2, v0
	v_subrev_u32_e32 v0, 32, v223
	v_cmp_lt_i32_e32 vcc, v0, v66
	s_add_i32 s2, s56, 1
	v_readlane_b32 s5, v248, 3
	v_cndmask_b32_e32 v0, v0, v223, vcc
	v_lshlrev_b32_e32 v230, 2, v0
	v_or_b32_e32 v0, v66, v135
	v_lshl_add_u64 v[66:67], v[132:133], 3, s[14:15]
	v_lshl_add_u64 v[142:143], v[66:67], 0, s[6:7]
	v_lshlrev_b64 v[66:67], 2, v[132:133]
	v_lshlrev_b32_e32 v231, 2, v0
	v_lshl_add_u64 v[68:69], s[14:15], 0, v[66:67]
	s_mov_b64 s[6:7], 0x26508000
	v_readlane_b32 s56, v251, 21
	v_lshlrev_b32_e32 v0, 2, v136
	v_ashrrev_i32_e32 v139, 3, v130
	v_bfe_u32 v227, v130, 4, 1
	v_lshl_add_u32 v233, v134, 2, s5
	v_lshl_add_u64 v[144:145], v[68:69], 0, s[6:7]
	s_movk_i32 s5, 0x210
	v_mul_u32_u24_e32 v68, 0x110, v135
	v_readlane_b32 s57, v251, 22
	v_readlane_b32 s64, v251, 29
	v_readlane_b32 s65, v251, 30
	v_readlane_b32 s36, v248, 35
	v_lshl_add_u64 v[148:149], s[0:1], 0, v[0:1]
	v_readlane_b32 s0, v248, 5
	s_mov_b32 s3, 0
	v_or_b32_e32 v232, 0xc0, v231
	v_cmp_eq_u32_e64 s[38:39], 0, v227
	v_cmp_eq_u32_e64 s[40:41], 0, v137
	v_mul_lo_u32 v234, v139, s5
	v_mul_u32_u24_e32 v235, 0x840, v137
	v_mul_lo_u32 v236, v226, s5
	v_or_b32_e32 v237, 64, v231
	v_or_b32_e32 v238, 0x80, v231
	v_readlane_b32 s37, v248, 36
	v_readlane_b32 s56, v248, 31
	v_lshl_add_u64 v[146:147], s[64:65], 0, v[66:67]
	v_add3_u32 v239, s0, v70, v68
	v_lshlrev_b32_e32 v150, 1, v140
	v_lshlrev_b32_e32 v152, 1, v134
	s_mov_b32 s5, 0
	v_readlane_b32 s12, v251, 0
	s_waitcnt lgkmcnt(0)
	s_barrier
	v_readlane_b32 s58, v251, 23
	v_readlane_b32 s59, v251, 24
	v_readlane_b32 s60, v251, 25
	v_readlane_b32 s61, v251, 26
	v_readlane_b32 s62, v251, 27
	v_readlane_b32 s63, v251, 28
	v_readlane_b32 s66, v251, 31
	v_readlane_b32 s67, v251, 32
	v_readlane_b32 s68, v251, 33
	v_readlane_b32 s69, v251, 34
	v_readlane_b32 s70, v251, 35
	v_readlane_b32 s71, v251, 36
	v_readlane_b32 s57, v248, 32
	s_waitcnt vmcnt(0)
	v_mul_f32_e32 v242, 0xbfb8aa3b, v179
	v_mul_f32_e32 v243, 0xbfb8aa3b, v224
	s_branch .LBB0_409

; __device__ __forceinline__ float mix_sigmoid(float v) { return __builtin_amdgcn_rcpf(1.0f + __expf(-v)); }
; __device__ __forceinline__ void mix_phase(LAS unsigned char* lds, const Params& p, const int layer) {
;     ...
;             for (int m = 0; m < 4; ++m) {
;                 float h_[4], P_[4];
; #pragma unroll
;                 for (int j = 0; j < 4; ++j) { const float xa = XC[(m * 16 + fq * 4 + j) * 132 + cw + fr];
;                     const float rg = mix_sigmoid(accr[m][j] + bav), ig = mix_sigmoid(acci[m][j] + bxv), la = -rg * c8v, x2 = 2.0f * la;
;                     const float Pj = __expf(la);
;                     const float q_ = 1.f + x2 * (0.5f + x2 * (1.f / 6 + x2 * (1.f / 24 + x2 * (1.f / 120 + x2 * (1.f / 720 + x2 * (1.f / 5040))))));
;                     const float om = (x2 > -0.3f) ? -x2 * q_ : 1.0f - Pj * Pj;
;                     P_[j] = Pj; h_[j] = __builtin_amdgcn_sqrtf(om) * (ig * xa); }
; #pragma unroll
;                 for (int j = 1; j < 4; ++j) { h_[j] = P_[j] * h_[j - 1] + h_[j]; P_[j] = P_[j] * P_[j - 1]; }
;                 float Pg = P_[3], Hg = h_[3];
;                 { const float Pu = __shfl_up(Pg, 16), Hu = __shfl_up(Hg, 16); if (gq >= 1) { Hg = Pg * Hu + Hg; Pg = Pg * Pu; } }
;                 { const float Pu = __shfl_up(Pg, 32), Hu = __shfl_up(Hg, 32); if (gq >= 2) { Hg = Pg * Hu + Hg; Pg = Pg * Pu; } }
;                 float Pe = __shfl_up(Pg, 16), He = __shfl_up(Hg, 16); if (gq == 0) { Pe = 1.f; He = 0.f; }
.LBB0_415:
	v_fmamk_f32 v102, v102, 0xbfb8aa3b, v242
	v_exp_f32_e32 v102, v102
	s_mul_i32 s0, s3, 0x8400
	s_add_i32 s6, s0, 0
	s_lshl_b32 s0, s35, 2
	v_add_f32_e32 v102, 1.0, v102
	v_rcp_f32_e64 v102, -v102
	s_add_i32 s0, s6, s0
	v_lshl_add_u32 v110, v135, 2, s0
	v_add_u32_e32 v151, v110, v235
	v_mul_f32_e32 v102, v225, v102
	ds_read_b32 v110, v151
	v_mul_f32_e32 v111, 0x3fb8aa3b, v102
	v_exp_f32_e32 v154, v111
	v_add_f32_e32 v102, v102, v102
	s_mov_b32 s0, 0xbe99999a
	v_cmp_nlt_f32_e32 vcc, s0, v102
	s_and_saveexec_b64 s[0:1], vcc
	s_xor_b64 s[0:1], exec, s[0:1]
	v_fma_f32 v111, -v154, v154, 1.0
	s_andn2_saveexec_b64 s[0:1], s[0:1]
	v_fmamk_f32 v111, v102, 0x39500d01, v217
	v_fmaak_f32 v111, v102, v111, 0x3c088889
	v_fmaak_f32 v111, v102, v111, 0x3d2aaaab
	v_fmaak_f32 v111, v102, v111, 0x3e2aaaab
	v_fma_f32 v111, v102, v111, 0.5
	v_fma_f32 v111, v102, v111, 1.0
	v_mul_f32_e64 v111, v111, -v102
	s_or_b64 exec, exec, s[0:1]
	v_fmamk_f32 v102, v103, 0xbfb8aa3b, v242
	v_exp_f32_e32 v102, v102
	ds_read_b32 v103, v151 offset:528
	s_mov_b32 s0, 0xbe99999a
	v_add_f32_e32 v102, 1.0, v102
	v_rcp_f32_e64 v102, -v102
	s_nop 0
	v_mul_f32_e32 v102, v225, v102
	v_mul_f32_e32 v112, 0x3fb8aa3b, v102
	v_exp_f32_e32 v112, v112
	v_add_f32_e32 v102, v102, v102
	v_cmp_nlt_f32_e32 vcc, s0, v102
	s_and_saveexec_b64 s[0:1], vcc
	s_xor_b64 s[0:1], exec, s[0:1]
	v_fma_f32 v113, -v112, v112, 1.0
	s_andn2_saveexec_b64 s[0:1], s[0:1]
	v_fmamk_f32 v113, v102, 0x39500d01, v217
	v_fmaak_f32 v113, v102, v113, 0x3c088889
	v_fmaak_f32 v113, v102, v113, 0x3d2aaaab
	v_fmaak_f32 v113, v102, v113, 0x3e2aaaab
	v_fma_f32 v113, v102, v113, 0.5
	v_fma_f32 v113, v102, v113, 1.0
	v_mul_f32_e64 v113, v113, -v102
	s_or_b64 exec, exec, s[0:1]
	v_fmamk_f32 v102, v104, 0xbfb8aa3b, v242
	v_exp_f32_e32 v102, v102
	ds_read_b32 v114, v151 offset:1056
	s_mov_b32 s0, 0xbe99999a
	v_add_f32_e32 v102, 1.0, v102
	v_rcp_f32_e64 v102, -v102
	s_nop 0
	v_mul_f32_e32 v102, v225, v102
	v_mul_f32_e32 v104, 0x3fb8aa3b, v102
	v_exp_f32_e32 v104, v104
	v_add_f32_e32 v102, v102, v102
	v_cmp_nlt_f32_e32 vcc, s0, v102
	s_and_saveexec_b64 s[0:1], vcc
	s_xor_b64 s[0:1], exec, s[0:1]
	v_fma_f32 v115, -v104, v104, 1.0
	s_andn2_saveexec_b64 s[0:1], s[0:1]
	v_fmamk_f32 v115, v102, 0x39500d01, v217
	v_fmaak_f32 v115, v102, v115, 0x3c088889
	v_fmaak_f32 v115, v102, v115, 0x3d2aaaab
	v_fmaak_f32 v115, v102, v115, 0x3e2aaaab
	v_fma_f32 v115, v102, v115, 0.5
	v_fma_f32 v115, v102, v115, 1.0
	v_mul_f32_e64 v115, v115, -v102
	s_or_b64 exec, exec, s[0:1]
	v_fmamk_f32 v102, v105, 0xbfb8aa3b, v242
	v_exp_f32_e32 v102, v102
	ds_read_b32 v105, v151 offset:1584
	s_mov_b32 s0, 0xbe99999a
	v_add_f32_e32 v102, 1.0, v102
	v_rcp_f32_e64 v102, -v102
	s_nop 0
	v_mul_f32_e32 v116, v225, v102
	v_mul_f32_e32 v102, 0x3fb8aa3b, v116
	v_exp_f32_e32 v102, v102
	v_add_f32_e32 v117, v116, v116
	v_cmp_nlt_f32_e32 vcc, s0, v117
	s_and_saveexec_b64 s[0:1], vcc
	s_xor_b64 s[0:1], exec, s[0:1]
	v_fma_f32 v116, -v102, v102, 1.0
	s_andn2_saveexec_b64 s[0:1], s[0:1]
	v_fmamk_f32 v116, v117, 0x39500d01, v217
	v_fmaak_f32 v116, v117, v116, 0x3c088889
	v_fmaak_f32 v116, v117, v116, 0x3d2aaaab
	v_fmaak_f32 v116, v117, v116, 0x3e2aaaab
	v_fma_f32 v116, v117, v116, 0.5
	v_fma_f32 v116, v117, v116, 1.0
	v_mul_f32_e64 v116, v116, -v117
	s_or_b64 exec, exec, s[0:1]
	v_fmamk_f32 v99, v99, 0xbfb8aa3b, v243
	v_exp_f32_e32 v99, v99
	v_fmamk_f32 v98, v98, 0xbfb8aa3b, v243
	v_fmamk_f32 v100, v100, 0xbfb8aa3b, v243
	v_exp_f32_e32 v98, v98
	v_exp_f32_e32 v100, v100
	v_fmamk_f32 v101, v101, 0xbfb8aa3b, v243
	v_exp_f32_e32 v101, v101
	v_add_f32_e32 v99, 1.0, v99
	v_rcp_f32_e32 v99, v99
	v_add_f32_e32 v98, 1.0, v98
	v_add_f32_e32 v100, 1.0, v100
	v_rcp_f32_e32 v98, v98
	v_rcp_f32_e32 v100, v100
	v_add_f32_e32 v101, 1.0, v101
	v_sqrt_f32_e32 v113, v113
	v_sqrt_f32_e32 v111, v111
	v_sqrt_f32_e32 v115, v115
	v_rcp_f32_e32 v101, v101
	s_waitcnt lgkmcnt(2)
	v_mul_f32_e32 v99, v99, v103
	v_sqrt_f32_e32 v103, v116
	v_mul_f32_e32 v98, v98, v110
	s_waitcnt lgkmcnt(1)
	v_mul_f32_e32 v100, v100, v114
	v_mul_f32_e32 v177, v99, v113
	v_mul_f32_e32 v176, v98, v111
	v_mul_f32_e32 v100, v100, v115
	s_waitcnt lgkmcnt(0)
	v_mul_f32_e32 v101, v101, v105
	v_fmac_f32_e32 v177, v112, v176
	v_mul_f32_e32 v155, v112, v154
	v_fmac_f32_e32 v100, v104, v177
	v_mul_f32_e32 v98, v103, v101
	v_mul_f32_e32 v104, v104, v155
	v_pk_fma_f32 v[98:99], v[102:103], v[100:101], v[98:99] op_sel_hi:[1,1,0]
	v_mul_f32_e32 v105, v102, v104
	ds_bpermute_b32 v99, v229, v98
	ds_bpermute_b32 v101, v229, v105
	v_cmp_eq_u32_e32 vcc, 0, v107
	v_cmp_lt_u32_e64 s[44:45], 1, v107
	s_waitcnt lgkmcnt(1)
	v_fma_f32 v99, v105, v99, v98
	s_waitcnt lgkmcnt(0)
	v_mul_f32_e32 v101, v105, v101
	v_cndmask_b32_e32 v99, v99, v98, vcc
	v_cndmask_b32_e32 v101, v101, v105, vcc
	ds_bpermute_b32 v102, v230, v99
	ds_bpermute_b32 v103, v230, v101
	v_fmamk_f32 v94, v94, 0xbfb8aa3b, v242
	v_exp_f32_e32 v94, v94
	s_mov_b32 s0, 0xbe99999a
	s_waitcnt lgkmcnt(1)
	v_fma_f32 v102, v101, v102, v99
	s_waitcnt lgkmcnt(0)
	v_mul_f32_e32 v103, v101, v103
	v_cndmask_b32_e64 v99, v99, v102, s[44:45]
	v_cndmask_b32_e64 v101, v101, v103, s[44:45]
	ds_bpermute_b32 v99, v229, v99
	ds_bpermute_b32 v101, v229, v101
	v_add_f32_e32 v94, 1.0, v94
	v_rcp_f32_e64 v94, -v94
	v_mov_b32_e32 v103, v98
	s_waitcnt lgkmcnt(1)
	v_cndmask_b32_e64 v178, v99, 0, vcc
	s_waitcnt lgkmcnt(0)
	v_cndmask_b32_e64 v158, v101, 1.0, vcc
	s_waitcnt vmcnt(3)
; __device__ __forceinline__ float mix_sigmoid(float v) { return __builtin_amdgcn_rcpf(1.0f + __expf(-v)); }
; __device__ __forceinline__ void mix_phase(LAS unsigned char* lds, const Params& p, const int layer) {
;     ...
;                 for (int j = 0; j < 4; ++j) { const float xa = XC[(m * 16 + fq * 4 + j) * 132 + cw + fr];
;                     const float rg = mix_sigmoid(accr[m][j] + bav), ig = mix_sigmoid(acci[m][j] + bxv), la = -rg * c8v, x2 = 2.0f * la;
;                     const float Pj = __expf(la);
;                     const float q_ = 1.f + x2 * (0.5f + x2 * (1.f / 6 + x2 * (1.f / 24 + x2 * (1.f / 120 + x2 * (1.f / 720 + x2 * (1.f / 5040))))));
;                     const float om = (x2 > -0.3f) ? -x2 * q_ : 1.0f - Pj * Pj;
;                     P_[j] = Pj; h_[j] = __builtin_amdgcn_sqrtf(om) * (ig * xa); }
; #pragma unroll
;                 for (int j = 1; j < 4; ++j) { h_[j] = P_[j] * h_[j - 1] + h_[j]; P_[j] = P_[j] * P_[j - 1]; }
;                 float Pg = P_[3], Hg = h_[3];
;                 { const float Pu = __shfl_up(Pg, 16), Hu = __shfl_up(Hg, 16); if (gq >= 1) { Hg = Pg * Hu + Hg; Pg = Pg * Pu; } }
;                 { const float Pu = __shfl_up(Pg, 32), Hu = __shfl_up(Hg, 32); if (gq >= 2) { Hg = Pg * Hu + Hg; Pg = Pg * Pu; } }
;                 float Pe = __shfl_up(Pg, 16), He = __shfl_up(Hg, 16); if (gq == 0) { Pe = 1.f; He = 0.f; }
;                 const float Hcm = prt ? Hc : h0s[m];
;                 const float Hin = Pe * Hcm + He, Pin = Pe * Pc;
; #pragma unroll
;                 for (int j = 0; j < 4; ++j) { hl[m][j] = h_[j] + P_[j] * Hin; pl[m][j] = P_[j] * Pin; }
;                 const float hb = __shfl(hl[m][3], 48 + fr), pb_ = __shfl(pl[m][3], 48 + fr);
;                 Hc = prt ? hb : 0.f; Pc = prt ? pb_ : 1.f;
	v_fmac_f32_e32 v178, v109, v158
	v_mul_f32_e32 v102, v104, v178
	v_mul_f32_e32 v101, v105, v178
	v_pk_add_f32 v[156:157], v[102:103], v[100:101]
	v_pk_mul_f32 v[160:161], v[104:105], v[158:159] op_sel_hi:[1,0]
	v_mul_f32_e32 v94, v225, v94
	ds_bpermute_b32 v98, v232, v157
	ds_bpermute_b32 v99, v232, v161
	ds_read_b32 v100, v151 offset:8448
	v_mul_f32_e32 v101, 0x3fb8aa3b, v94
	v_exp_f32_e32 v162, v101
	v_add_f32_e32 v94, v94, v94
	v_cmp_nlt_f32_e64 s[0:1], s0, v94
	s_and_saveexec_b64 s[14:15], s[0:1]
	s_xor_b64 s[0:1], exec, s[14:15]
	v_fma_f32 v101, -v162, v162, 1.0
	s_andn2_saveexec_b64 s[0:1], s[0:1]
	v_fmamk_f32 v101, v94, 0x39500d01, v217
	v_fmaak_f32 v101, v94, v101, 0x3c088889
	v_fmaak_f32 v101, v94, v101, 0x3d2aaaab
	v_fmaak_f32 v101, v94, v101, 0x3e2aaaab
	v_fma_f32 v101, v94, v101, 0.5
	v_fma_f32 v101, v94, v101, 1.0
	v_mul_f32_e64 v101, v101, -v94
	s_or_b64 exec, exec, s[0:1]
	v_fmamk_f32 v94, v95, 0xbfb8aa3b, v242
	v_exp_f32_e32 v94, v94
	ds_read_b32 v95, v151 offset:8976
	s_mov_b32 s0, 0xbe99999a
	v_add_f32_e32 v94, 1.0, v94
	v_rcp_f32_e64 v94, -v94
	s_nop 0
	v_mul_f32_e32 v94, v225, v94
	v_mul_f32_e32 v102, 0x3fb8aa3b, v94
	v_exp_f32_e32 v102, v102
	v_add_f32_e32 v94, v94, v94
	v_cmp_nlt_f32_e64 s[0:1], s0, v94
	s_and_saveexec_b64 s[14:15], s[0:1]
	s_xor_b64 s[0:1], exec, s[14:15]
	v_fma_f32 v103, -v102, v102, 1.0
	s_andn2_saveexec_b64 s[0:1], s[0:1]
	v_fmamk_f32 v103, v94, 0x39500d01, v217
	v_fmaak_f32 v103, v94, v103, 0x3c088889
	v_fmaak_f32 v103, v94, v103, 0x3d2aaaab
	v_fmaak_f32 v103, v94, v103, 0x3e2aaaab
	v_fma_f32 v103, v94, v103, 0.5
	v_fma_f32 v103, v94, v103, 1.0
	v_mul_f32_e64 v103, v103, -v94
	s_or_b64 exec, exec, s[0:1]
	v_fmamk_f32 v94, v96, 0xbfb8aa3b, v242
	v_exp_f32_e32 v94, v94
	ds_read_b32 v104, v151 offset:9504
	s_mov_b32 s0, 0xbe99999a
	v_add_f32_e32 v94, 1.0, v94
	v_rcp_f32_e64 v94, -v94
	s_nop 0
	v_mul_f32_e32 v94, v225, v94
	v_mul_f32_e32 v96, 0x3fb8aa3b, v94
	v_exp_f32_e32 v96, v96
	v_add_f32_e32 v94, v94, v94
	v_cmp_nlt_f32_e64 s[0:1], s0, v94
	s_and_saveexec_b64 s[14:15], s[0:1]
	s_xor_b64 s[0:1], exec, s[14:15]
	v_fma_f32 v105, -v96, v96, 1.0
	s_andn2_saveexec_b64 s[0:1], s[0:1]
	v_fmamk_f32 v105, v94, 0x39500d01, v217
	v_fmaak_f32 v105, v94, v105, 0x3c088889
	v_fmaak_f32 v105, v94, v105, 0x3d2aaaab
	v_fmaak_f32 v105, v94, v105, 0x3e2aaaab
	v_fma_f32 v105, v94, v105, 0.5
	v_fma_f32 v105, v94, v105, 1.0
	v_mul_f32_e64 v105, v105, -v94
	s_or_b64 exec, exec, s[0:1]
	v_fmamk_f32 v94, v97, 0xbfb8aa3b, v242
	v_exp_f32_e32 v94, v94
	ds_read_b32 v97, v151 offset:10032
	s_mov_b32 s0, 0xbe99999a
	v_add_f32_e32 v94, 1.0, v94
	v_rcp_f32_e64 v94, -v94
	s_nop 0
	v_mul_f32_e32 v107, v225, v94
	v_mul_f32_e32 v94, 0x3fb8aa3b, v107
	v_exp_f32_e32 v94, v94
	v_add_f32_e32 v109, v107, v107
	v_cmp_nlt_f32_e64 s[0:1], s0, v109
	s_and_saveexec_b64 s[14:15], s[0:1]
	s_xor_b64 s[0:1], exec, s[14:15]
	v_fma_f32 v107, -v94, v94, 1.0
	s_andn2_saveexec_b64 s[0:1], s[0:1]
	v_fmamk_f32 v107, v109, 0x39500d01, v217
	v_fmaak_f32 v107, v109, v107, 0x3c088889
	v_fmaak_f32 v107, v109, v107, 0x3d2aaaab
	v_fmaak_f32 v107, v109, v107, 0x3e2aaaab
	v_fma_f32 v107, v109, v107, 0.5
	v_fma_f32 v107, v109, v107, 1.0
	v_mul_f32_e64 v107, v107, -v109
	s_or_b64 exec, exec, s[0:1]
	v_fmamk_f32 v91, v91, 0xbfb8aa3b, v243
	v_exp_f32_e32 v91, v91
	v_fmamk_f32 v90, v90, 0xbfb8aa3b, v243
	v_fmamk_f32 v92, v92, 0xbfb8aa3b, v243
	v_exp_f32_e32 v90, v90
	v_exp_f32_e32 v92, v92
	v_fmamk_f32 v93, v93, 0xbfb8aa3b, v243
	v_exp_f32_e32 v93, v93
	v_add_f32_e32 v91, 1.0, v91
	v_rcp_f32_e32 v91, v91
	v_add_f32_e32 v90, 1.0, v90
	v_add_f32_e32 v92, 1.0, v92
	v_rcp_f32_e32 v90, v90
	v_rcp_f32_e32 v92, v92
	v_add_f32_e32 v93, 1.0, v93
	v_sqrt_f32_e32 v103, v103
	v_sqrt_f32_e32 v101, v101
	v_sqrt_f32_e32 v105, v105
	v_rcp_f32_e32 v93, v93
	s_waitcnt lgkmcnt(2)
	v_mul_f32_e32 v91, v91, v95
	v_sqrt_f32_e32 v95, v107
	v_mul_f32_e32 v90, v90, v100
	s_waitcnt lgkmcnt(1)
	v_mul_f32_e32 v92, v92, v104
	v_mul_f32_e32 v189, v91, v103
	v_mul_f32_e32 v188, v90, v101
	v_mul_f32_e32 v92, v92, v105
	s_waitcnt lgkmcnt(0)
	v_mul_f32_e32 v93, v93, v97
	v_fmac_f32_e32 v189, v102, v188
	v_mul_f32_e32 v163, v102, v162
	v_fmac_f32_e32 v92, v96, v189
	v_mul_f32_e32 v90, v95, v93
	v_mul_f32_e32 v96, v96, v163
	v_pk_fma_f32 v[90:91], v[94:95], v[92:93], v[90:91] op_sel_hi:[1,1,0]
	v_mul_f32_e32 v97, v94, v96
	ds_bpermute_b32 v91, v229, v90
	ds_bpermute_b32 v93, v229, v97
	v_fmamk_f32 v86, v86, 0xbfb8aa3b, v242
	v_exp_f32_e32 v86, v86
	s_waitcnt lgkmcnt(1)
	v_fma_f32 v91, v97, v91, v90
	s_waitcnt lgkmcnt(0)
	v_mul_f32_e32 v93, v97, v93
	v_cndmask_b32_e32 v91, v91, v90, vcc
	v_cndmask_b32_e32 v93, v93, v97, vcc
	ds_bpermute_b32 v94, v230, v91
	ds_bpermute_b32 v95, v230, v93
	v_add_f32_e32 v86, 1.0, v86
	v_rcp_f32_e64 v86, -v86
	s_mov_b32 s0, 0xbe99999a
	s_waitcnt lgkmcnt(1)
	v_fma_f32 v94, v93, v94, v91
	s_waitcnt lgkmcnt(0)
	v_mul_f32_e32 v95, v93, v95
	v_cndmask_b32_e64 v91, v91, v94, s[44:45]
	v_cndmask_b32_e64 v93, v93, v95, s[44:45]
	ds_bpermute_b32 v91, v229, v91
	ds_bpermute_b32 v93, v229, v93
	s_waitcnt vmcnt(2)
	v_cndmask_b32_e64 v95, v108, v98, s[42:43]
	v_cndmask_b32_e64 v94, 1.0, v99, s[42:43]
	v_mul_f32_e32 v86, v225, v86
	s_waitcnt lgkmcnt(1)
	v_cndmask_b32_e64 v192, v91, 0, vcc
	s_waitcnt lgkmcnt(0)
; __device__ __forceinline__ float mix_sigmoid(float v) { return __builtin_amdgcn_rcpf(1.0f + __expf(-v)); }
; __device__ __forceinline__ void mix_phase(LAS unsigned char* lds, const Params& p, const int layer) {
;     ...
;                 for (int j = 0; j < 4; ++j) { const float xa = XC[(m * 16 + fq * 4 + j) * 132 + cw + fr];
;                     const float rg = mix_sigmoid(accr[m][j] + bav), ig = mix_sigmoid(acci[m][j] + bxv), la = -rg * c8v, x2 = 2.0f * la;
;                     const float Pj = __expf(la);
;                     const float q_ = 1.f + x2 * (0.5f + x2 * (1.f / 6 + x2 * (1.f / 24 + x2 * (1.f / 120 + x2 * (1.f / 720 + x2 * (1.f / 5040))))));
;                     const float om = (x2 > -0.3f) ? -x2 * q_ : 1.0f - Pj * Pj;
;                     P_[j] = Pj; h_[j] = __builtin_amdgcn_sqrtf(om) * (ig * xa); }
; #pragma unroll
;                 for (int j = 1; j < 4; ++j) { h_[j] = P_[j] * h_[j - 1] + h_[j]; P_[j] = P_[j] * P_[j - 1]; }
;                 float Pg = P_[3], Hg = h_[3];
;                 { const float Pu = __shfl_up(Pg, 16), Hu = __shfl_up(Hg, 16); if (gq >= 1) { Hg = Pg * Hu + Hg; Pg = Pg * Pu; } }
;                 { const float Pu = __shfl_up(Pg, 32), Hu = __shfl_up(Hg, 32); if (gq >= 2) { Hg = Pg * Hu + Hg; Pg = Pg * Pu; } }
;                 float Pe = __shfl_up(Pg, 16), He = __shfl_up(Hg, 16); if (gq == 0) { Pe = 1.f; He = 0.f; }
;                 const float Hcm = prt ? Hc : h0s[m];
;                 const float Hin = Pe * Hcm + He, Pin = Pe * Pc;
; #pragma unroll
;                 for (int j = 0; j < 4; ++j) { hl[m][j] = h_[j] + P_[j] * Hin; pl[m][j] = P_[j] * Pin; }
;                 const float hb = __shfl(hl[m][3], 48 + fr), pb_ = __shfl(pl[m][3], 48 + fr);
;                 Hc = prt ? hb : 0.f; Pc = prt ? pb_ : 1.f;
	v_cndmask_b32_e64 v91, v93, 1.0, vcc
	v_fmac_f32_e32 v192, v95, v91
	v_mul_f32_e32 v170, v94, v91
	v_mul_f32_e32 v94, v96, v192
	v_mul_f32_e32 v93, v97, v192
	v_mov_b32_e32 v95, v90
	v_pk_add_f32 v[168:169], v[94:95], v[92:93]
	v_pk_mul_f32 v[172:173], v[96:97], v[170:171] op_sel_hi:[1,0]
	ds_bpermute_b32 v90, v232, v169
	ds_bpermute_b32 v91, v232, v173
	ds_read_b32 v92, v151 offset:16896
	v_mul_f32_e32 v93, 0x3fb8aa3b, v86
	v_exp_f32_e32 v174, v93
	v_add_f32_e32 v86, v86, v86
	v_cmp_nlt_f32_e64 s[0:1], s0, v86
	s_and_saveexec_b64 s[14:15], s[0:1]
	s_xor_b64 s[0:1], exec, s[14:15]
	v_fma_f32 v93, -v174, v174, 1.0
	s_andn2_saveexec_b64 s[0:1], s[0:1]
	v_fmamk_f32 v93, v86, 0x39500d01, v217
	v_fmaak_f32 v93, v86, v93, 0x3c088889
	v_fmaak_f32 v93, v86, v93, 0x3d2aaaab
	v_fmaak_f32 v93, v86, v93, 0x3e2aaaab
	v_fma_f32 v93, v86, v93, 0.5
	v_fma_f32 v93, v86, v93, 1.0
	v_mul_f32_e64 v93, v93, -v86
	s_or_b64 exec, exec, s[0:1]
	v_fmamk_f32 v86, v87, 0xbfb8aa3b, v242
	v_exp_f32_e32 v86, v86
	ds_read_b32 v87, v151 offset:17424
	s_mov_b32 s0, 0xbe99999a
	v_add_f32_e32 v86, 1.0, v86
	v_rcp_f32_e64 v86, -v86
	s_nop 0
	v_mul_f32_e32 v86, v225, v86
	v_mul_f32_e32 v94, 0x3fb8aa3b, v86
	v_exp_f32_e32 v94, v94
	v_add_f32_e32 v86, v86, v86
	v_cmp_nlt_f32_e64 s[0:1], s0, v86
	s_and_saveexec_b64 s[14:15], s[0:1]
	s_xor_b64 s[0:1], exec, s[14:15]
	v_fma_f32 v95, -v94, v94, 1.0
	s_andn2_saveexec_b64 s[0:1], s[0:1]
	v_fmamk_f32 v95, v86, 0x39500d01, v217
	v_fmaak_f32 v95, v86, v95, 0x3c088889
	v_fmaak_f32 v95, v86, v95, 0x3d2aaaab
	v_fmaak_f32 v95, v86, v95, 0x3e2aaaab
	v_fma_f32 v95, v86, v95, 0.5
	v_fma_f32 v95, v86, v95, 1.0
	v_mul_f32_e64 v95, v95, -v86
	s_or_b64 exec, exec, s[0:1]
	v_fmamk_f32 v86, v88, 0xbfb8aa3b, v242
	v_exp_f32_e32 v86, v86
	ds_read_b32 v96, v151 offset:17952
	s_mov_b32 s0, 0xbe99999a
	v_add_f32_e32 v86, 1.0, v86
	v_rcp_f32_e64 v86, -v86
	s_nop 0
	v_mul_f32_e32 v86, v225, v86
	v_mul_f32_e32 v88, 0x3fb8aa3b, v86
	v_exp_f32_e32 v88, v88
	v_add_f32_e32 v86, v86, v86
	v_cmp_nlt_f32_e64 s[0:1], s0, v86
	s_and_saveexec_b64 s[14:15], s[0:1]
	s_xor_b64 s[0:1], exec, s[14:15]
	v_fma_f32 v97, -v88, v88, 1.0
	s_andn2_saveexec_b64 s[0:1], s[0:1]
	v_fmamk_f32 v97, v86, 0x39500d01, v217
	v_fmaak_f32 v97, v86, v97, 0x3c088889
	v_fmaak_f32 v97, v86, v97, 0x3d2aaaab
	v_fmaak_f32 v97, v86, v97, 0x3e2aaaab
	v_fma_f32 v97, v86, v97, 0.5
	v_fma_f32 v97, v86, v97, 1.0
	v_mul_f32_e64 v97, v97, -v86
	s_or_b64 exec, exec, s[0:1]
	v_fmamk_f32 v86, v89, 0xbfb8aa3b, v242
	v_exp_f32_e32 v86, v86
	ds_read_b32 v89, v151 offset:18480
	s_mov_b32 s0, 0xbe99999a
	v_add_f32_e32 v86, 1.0, v86
	v_rcp_f32_e64 v86, -v86
	s_nop 0
	v_mul_f32_e32 v98, v225, v86
	v_mul_f32_e32 v86, 0x3fb8aa3b, v98
	v_exp_f32_e32 v86, v86
	v_add_f32_e32 v99, v98, v98
	v_cmp_nlt_f32_e64 s[0:1], s0, v99
	s_and_saveexec_b64 s[14:15], s[0:1]
	s_xor_b64 s[0:1], exec, s[14:15]
	v_fma_f32 v98, -v86, v86, 1.0
	s_andn2_saveexec_b64 s[0:1], s[0:1]
	v_fmamk_f32 v98, v99, 0x39500d01, v217
	v_fmaak_f32 v98, v99, v98, 0x3c088889
	v_fmaak_f32 v98, v99, v98, 0x3d2aaaab
	v_fmaak_f32 v98, v99, v98, 0x3e2aaaab
	v_fma_f32 v98, v99, v98, 0.5
	v_fma_f32 v98, v99, v98, 1.0
	v_mul_f32_e64 v98, v98, -v99
	s_or_b64 exec, exec, s[0:1]
	v_fmamk_f32 v83, v83, 0xbfb8aa3b, v243
	v_exp_f32_e32 v83, v83
	v_fmamk_f32 v82, v82, 0xbfb8aa3b, v243
	v_fmamk_f32 v84, v84, 0xbfb8aa3b, v243
	v_exp_f32_e32 v82, v82
	v_exp_f32_e32 v84, v84
	v_fmamk_f32 v85, v85, 0xbfb8aa3b, v243
	v_exp_f32_e32 v85, v85
	v_add_f32_e32 v83, 1.0, v83
	v_rcp_f32_e32 v83, v83
	v_add_f32_e32 v82, 1.0, v82
	v_add_f32_e32 v84, 1.0, v84
	v_rcp_f32_e32 v82, v82
	v_rcp_f32_e32 v84, v84
	v_add_f32_e32 v85, 1.0, v85
	v_sqrt_f32_e32 v95, v95
	v_sqrt_f32_e32 v93, v93
	v_sqrt_f32_e32 v97, v97
	v_rcp_f32_e32 v85, v85
	s_waitcnt lgkmcnt(2)
	v_mul_f32_e32 v83, v83, v87
	v_sqrt_f32_e32 v87, v98
	v_mul_f32_e32 v82, v82, v92
	s_waitcnt lgkmcnt(1)
	v_mul_f32_e32 v84, v84, v96
	v_mul_f32_e32 v201, v83, v95
	v_mul_f32_e32 v200, v82, v93
	v_mul_f32_e32 v84, v84, v97
	s_waitcnt lgkmcnt(0)
	v_mul_f32_e32 v85, v85, v89
	v_fmac_f32_e32 v201, v94, v200
	v_mul_f32_e32 v175, v94, v174
	v_fmac_f32_e32 v84, v88, v201
	v_mul_f32_e32 v82, v87, v85
	v_mul_f32_e32 v88, v88, v175
	v_pk_fma_f32 v[82:83], v[86:87], v[84:85], v[82:83] op_sel_hi:[1,1,0]
	v_mul_f32_e32 v89, v86, v88
	ds_bpermute_b32 v83, v229, v82
	ds_bpermute_b32 v85, v229, v89
	v_fmamk_f32 v78, v78, 0xbfb8aa3b, v242
	v_exp_f32_e32 v78, v78
	s_waitcnt lgkmcnt(1)
	v_fma_f32 v83, v89, v83, v82
	s_waitcnt lgkmcnt(0)
	v_mul_f32_e32 v85, v89, v85
	v_cndmask_b32_e32 v83, v83, v82, vcc
	v_cndmask_b32_e32 v85, v85, v89, vcc
	ds_bpermute_b32 v86, v230, v83
	ds_bpermute_b32 v87, v230, v85
	v_add_f32_e32 v78, 1.0, v78
	v_rcp_f32_e64 v78, -v78
	s_mov_b32 s0, 0xbe99999a
	s_waitcnt lgkmcnt(1)
	v_fma_f32 v86, v85, v86, v83
	s_waitcnt lgkmcnt(0)
	v_mul_f32_e32 v87, v85, v87
	v_cndmask_b32_e64 v83, v83, v86, s[44:45]
	v_cndmask_b32_e64 v85, v85, v87, s[44:45]
	ds_bpermute_b32 v83, v229, v83
	ds_bpermute_b32 v85, v229, v85
	s_waitcnt vmcnt(1)
	v_cndmask_b32_e64 v87, v106, v90, s[42:43]
	v_cndmask_b32_e64 v86, 1.0, v91, s[42:43]
	v_mul_f32_e32 v78, v225, v78
	s_waitcnt lgkmcnt(1)
	v_cndmask_b32_e64 v202, v83, 0, vcc
	s_waitcnt lgkmcnt(0)
; __device__ __forceinline__ float mix_sigmoid(float v) { return __builtin_amdgcn_rcpf(1.0f + __expf(-v)); }
; __device__ __forceinline__ void mix_phase(LAS unsigned char* lds, const Params& p, const int layer) {
;     ...
;                 for (int j = 0; j < 4; ++j) { const float xa = XC[(m * 16 + fq * 4 + j) * 132 + cw + fr];
;                     const float rg = mix_sigmoid(accr[m][j] + bav), ig = mix_sigmoid(acci[m][j] + bxv), la = -rg * c8v, x2 = 2.0f * la;
;                     const float Pj = __expf(la);
;                     const float q_ = 1.f + x2 * (0.5f + x2 * (1.f / 6 + x2 * (1.f / 24 + x2 * (1.f / 120 + x2 * (1.f / 720 + x2 * (1.f / 5040))))));
;                     const float om = (x2 > -0.3f) ? -x2 * q_ : 1.0f - Pj * Pj;
;                     P_[j] = Pj; h_[j] = __builtin_amdgcn_sqrtf(om) * (ig * xa); }
; #pragma unroll
;                 for (int j = 1; j < 4; ++j) { h_[j] = P_[j] * h_[j - 1] + h_[j]; P_[j] = P_[j] * P_[j - 1]; }
;                 float Pg = P_[3], Hg = h_[3];
;                 { const float Pu = __shfl_up(Pg, 16), Hu = __shfl_up(Hg, 16); if (gq >= 1) { Hg = Pg * Hu + Hg; Pg = Pg * Pu; } }
;                 { const float Pu = __shfl_up(Pg, 32), Hu = __shfl_up(Hg, 32); if (gq >= 2) { Hg = Pg * Hu + Hg; Pg = Pg * Pu; } }
;                 float Pe = __shfl_up(Pg, 16), He = __shfl_up(Hg, 16); if (gq == 0) { Pe = 1.f; He = 0.f; }
;                 const float Hcm = prt ? Hc : h0s[m];
;                 const float Hin = Pe * Hcm + He, Pin = Pe * Pc;
; #pragma unroll
;                 for (int j = 0; j < 4; ++j) { hl[m][j] = h_[j] + P_[j] * Hin; pl[m][j] = P_[j] * Pin; }
;                 const float hb = __shfl(hl[m][3], 48 + fr), pb_ = __shfl(pl[m][3], 48 + fr);
;                 Hc = prt ? hb : 0.f; Pc = prt ? pb_ : 1.f;
;             }
;             if (!prt && (fq & 1)) {
; #pragma unroll
;                 for (int m = 0; m < 4; ++m) out[O_HS + (size_t)(layer * 128 + ((r0 - NP) >> 3) + 2 * m + (fq >> 1)) * LW + ch] = hl[m][3];
	v_cndmask_b32_e64 v83, v85, 1.0, vcc
	v_fmac_f32_e32 v202, v87, v83
	v_mul_f32_e32 v182, v86, v83
	v_mul_f32_e32 v86, v88, v202
	v_mul_f32_e32 v85, v89, v202
	v_mov_b32_e32 v87, v82
	v_pk_add_f32 v[180:181], v[86:87], v[84:85]
	v_pk_mul_f32 v[184:185], v[88:89], v[182:183] op_sel_hi:[1,0]
	ds_bpermute_b32 v82, v232, v181
	ds_bpermute_b32 v83, v232, v185
	ds_read_b32 v84, v151 offset:25344
	v_mul_f32_e32 v85, 0x3fb8aa3b, v78
	v_exp_f32_e32 v186, v85
	v_add_f32_e32 v78, v78, v78
	v_cmp_nlt_f32_e64 s[0:1], s0, v78
	s_and_saveexec_b64 s[14:15], s[0:1]
	s_xor_b64 s[0:1], exec, s[14:15]
	v_fma_f32 v85, -v186, v186, 1.0
	s_andn2_saveexec_b64 s[0:1], s[0:1]
	v_fmamk_f32 v85, v78, 0x39500d01, v217
	v_fmaak_f32 v85, v78, v85, 0x3c088889
	v_fmaak_f32 v85, v78, v85, 0x3d2aaaab
	v_fmaak_f32 v85, v78, v85, 0x3e2aaaab
	v_fma_f32 v85, v78, v85, 0.5
	v_fma_f32 v85, v78, v85, 1.0
	v_mul_f32_e64 v85, v85, -v78
	s_or_b64 exec, exec, s[0:1]
	v_fmamk_f32 v78, v79, 0xbfb8aa3b, v242
	v_exp_f32_e32 v78, v78
	ds_read_b32 v79, v151 offset:25872
	s_mov_b32 s0, 0xbe99999a
	v_add_f32_e32 v78, 1.0, v78
	v_rcp_f32_e64 v78, -v78
	s_nop 0
	v_mul_f32_e32 v78, v225, v78
	v_mul_f32_e32 v86, 0x3fb8aa3b, v78
	v_exp_f32_e32 v86, v86
	v_add_f32_e32 v78, v78, v78
	v_cmp_nlt_f32_e64 s[0:1], s0, v78
	s_and_saveexec_b64 s[14:15], s[0:1]
	s_xor_b64 s[0:1], exec, s[14:15]
	v_fma_f32 v87, -v86, v86, 1.0
	s_andn2_saveexec_b64 s[0:1], s[0:1]
	v_fmamk_f32 v87, v78, 0x39500d01, v217
	v_fmaak_f32 v87, v78, v87, 0x3c088889
	v_fmaak_f32 v87, v78, v87, 0x3d2aaaab
	v_fmaak_f32 v87, v78, v87, 0x3e2aaaab
	v_fma_f32 v87, v78, v87, 0.5
	v_fma_f32 v87, v78, v87, 1.0
	v_mul_f32_e64 v87, v87, -v78
	s_or_b64 exec, exec, s[0:1]
	v_fmamk_f32 v78, v80, 0xbfb8aa3b, v242
	v_exp_f32_e32 v78, v78
	ds_read_b32 v88, v151 offset:26400
	s_mov_b32 s0, 0xbe99999a
	v_add_f32_e32 v78, 1.0, v78
	v_rcp_f32_e64 v78, -v78
	s_nop 0
	v_mul_f32_e32 v78, v225, v78
	v_mul_f32_e32 v80, 0x3fb8aa3b, v78
	v_exp_f32_e32 v80, v80
	v_add_f32_e32 v78, v78, v78
	v_cmp_nlt_f32_e64 s[0:1], s0, v78
	s_and_saveexec_b64 s[14:15], s[0:1]
	s_xor_b64 s[0:1], exec, s[14:15]
	v_fma_f32 v89, -v80, v80, 1.0
	s_andn2_saveexec_b64 s[0:1], s[0:1]
	v_fmamk_f32 v89, v78, 0x39500d01, v217
	v_fmaak_f32 v89, v78, v89, 0x3c088889
	v_fmaak_f32 v89, v78, v89, 0x3d2aaaab
	v_fmaak_f32 v89, v78, v89, 0x3e2aaaab
	v_fma_f32 v89, v78, v89, 0.5
	v_fma_f32 v89, v78, v89, 1.0
	v_mul_f32_e64 v89, v89, -v78
	s_or_b64 exec, exec, s[0:1]
	v_fmamk_f32 v78, v81, 0xbfb8aa3b, v242
	v_exp_f32_e32 v78, v78
	ds_read_b32 v81, v151 offset:26928
	s_mov_b32 s0, 0xbe99999a
	v_add_f32_e32 v78, 1.0, v78
	v_rcp_f32_e64 v78, -v78
	s_nop 0
	v_mul_f32_e32 v90, v225, v78
	v_mul_f32_e32 v78, 0x3fb8aa3b, v90
	v_exp_f32_e32 v78, v78
	v_add_f32_e32 v91, v90, v90
	v_cmp_nlt_f32_e64 s[0:1], s0, v91
	s_and_saveexec_b64 s[14:15], s[0:1]
	s_xor_b64 s[0:1], exec, s[14:15]
	v_fma_f32 v90, -v78, v78, 1.0
	s_andn2_saveexec_b64 s[0:1], s[0:1]
	v_fmamk_f32 v90, v91, 0x39500d01, v217
	v_fmaak_f32 v90, v91, v90, 0x3c088889
	v_fmaak_f32 v90, v91, v90, 0x3d2aaaab
	v_fmaak_f32 v90, v91, v90, 0x3e2aaaab
	v_fma_f32 v90, v91, v90, 0.5
	v_fma_f32 v90, v91, v90, 1.0
	v_mul_f32_e64 v90, v90, -v91
	s_or_b64 exec, exec, s[0:1]
	v_fmamk_f32 v75, v75, 0xbfb8aa3b, v243
	v_exp_f32_e32 v75, v75
	v_fmamk_f32 v74, v74, 0xbfb8aa3b, v243
	v_fmamk_f32 v76, v76, 0xbfb8aa3b, v243
	v_exp_f32_e32 v74, v74
	v_exp_f32_e32 v76, v76
	v_fmamk_f32 v77, v77, 0xbfb8aa3b, v243
	v_exp_f32_e32 v77, v77
	v_add_f32_e32 v75, 1.0, v75
	v_rcp_f32_e32 v75, v75
	v_add_f32_e32 v74, 1.0, v74
	v_add_f32_e32 v76, 1.0, v76
	v_rcp_f32_e32 v74, v74
	v_rcp_f32_e32 v76, v76
	v_add_f32_e32 v77, 1.0, v77
	v_sqrt_f32_e32 v87, v87
	v_sqrt_f32_e32 v85, v85
	v_sqrt_f32_e32 v89, v89
	v_rcp_f32_e32 v77, v77
	s_waitcnt lgkmcnt(2)
	v_mul_f32_e32 v75, v75, v79
	v_sqrt_f32_e32 v79, v90
	v_mul_f32_e32 v74, v74, v84
	s_waitcnt lgkmcnt(1)
	v_mul_f32_e32 v76, v76, v88
	v_mul_f32_e32 v205, v75, v87
	v_mul_f32_e32 v204, v74, v85
	v_mul_f32_e32 v76, v76, v89
	s_waitcnt lgkmcnt(0)
	v_mul_f32_e32 v77, v77, v81
	v_fmac_f32_e32 v205, v86, v204
	v_mul_f32_e32 v187, v86, v186
	v_fmac_f32_e32 v76, v80, v205
	v_mul_f32_e32 v74, v79, v77
	v_mul_f32_e32 v80, v80, v187
	v_pk_fma_f32 v[74:75], v[78:79], v[76:77], v[74:75] op_sel_hi:[1,1,0]
	v_mul_f32_e32 v81, v78, v80
	ds_bpermute_b32 v75, v229, v74
	ds_bpermute_b32 v77, v229, v81
	s_waitcnt vmcnt(0)
	v_cndmask_b32_e64 v0, v0, v82, s[42:43]
	s_nor_b64 s[14:15], s[42:43], s[38:39]
	s_waitcnt lgkmcnt(1)
	v_fma_f32 v75, v81, v75, v74
	s_waitcnt lgkmcnt(0)
	v_mul_f32_e32 v77, v81, v77
	v_cndmask_b32_e32 v75, v75, v74, vcc
	v_cndmask_b32_e32 v77, v77, v81, vcc
	ds_bpermute_b32 v78, v230, v75
	ds_bpermute_b32 v79, v230, v77
	s_waitcnt lgkmcnt(1)
	v_fma_f32 v78, v77, v78, v75
	s_waitcnt lgkmcnt(0)
	v_mul_f32_e32 v79, v77, v79
	v_cndmask_b32_e64 v75, v75, v78, s[44:45]
	v_cndmask_b32_e64 v77, v77, v79, s[44:45]
	ds_bpermute_b32 v75, v229, v75
	ds_bpermute_b32 v77, v229, v77
	v_cndmask_b32_e64 v78, 1.0, v83, s[42:43]
	v_mov_b32_e32 v79, v74
	s_waitcnt lgkmcnt(1)
	v_cndmask_b32_e64 v206, v75, 0, vcc
	s_waitcnt lgkmcnt(0)
	v_cndmask_b32_e64 v75, v77, 1.0, vcc
	v_fmac_f32_e32 v206, v0, v75
	v_mul_f32_e32 v196, v78, v75
	v_mul_f32_e32 v78, v80, v206
	v_mul_f32_e32 v77, v81, v206
	v_pk_add_f32 v[190:191], v[78:79], v[76:77]
	v_pk_mul_f32 v[194:195], v[80:81], v[196:197] op_sel_hi:[1,0]
	ds_bpermute_b32 v199, v232, v191
	ds_bpermute_b32 v241, v232, v195
	s_and_saveexec_b64 s[0:1], s[14:15]
	s_cbranch_execz .LBB0_481
	s_add_i32 s13, s7, 0xffffe000
	s_ashr_i32 s13, s13, 3
	v_add_u32_e32 v74, s13, v228
	v_ashrrev_i32_e32 v75, 31, v74
	v_readlane_b32 s44, v251, 1
	v_lshlrev_b64 v[74:75], 13, v[74:75]
	v_readlane_b32 s46, v251, 3
	v_readlane_b32 s47, v251, 4
	v_readlane_b32 s45, v251, 2
	v_readlane_b32 s48, v251, 5
	v_lshl_add_u64 v[74:75], s[46:47], 0, v[74:75]
	v_lshl_add_u64 v[74:75], v[132:133], 2, v[74:75]
	v_add_co_u32_e32 v76, vcc, 0x5db8000, v74
	v_readlane_b32 s49, v251, 6
	s_nop 0
	v_addc_co_u32_e32 v77, vcc, 0, v75, vcc
	global_store_dword v[76:77], v157, off
	v_add_co_u32_e32 v76, vcc, 0x5dbc000, v74
	v_readlane_b32 s50, v251, 7
	s_nop 0
	v_addc_co_u32_e32 v77, vcc, 0, v75, vcc
	global_store_dword v[76:77], v169, off
	v_add_co_u32_e32 v76, vcc, 0x5dc0000, v74
	v_readlane_b32 s51, v251, 8
	s_nop 0
	v_addc_co_u32_e32 v77, vcc, 0, v75, vcc
	v_add_co_u32_e32 v74, vcc, 0x5dc4000, v74
	global_store_dword v[76:77], v181, off
	s_nop 0
	v_addc_co_u32_e32 v75, vcc, 0, v75, vcc
	global_store_dword v[74:75], v191, off
